# adds EpiGlu (phase 5) epilogue rewrite: loads issued together + LDS transpose to row-friendly accesses
# speedup vs baseline: 1.0524x; 1.0031x over previous
.LBB0_1407:
	v_and_b32_e32 v128, 63, v180
	v_and_b32_e32 v129, 15, v180
	v_bfe_u32 v130, v180, 4, 2
	v_lshrrev_b32_e32 v131, 6, v180
	v_lshlrev_b32_e32 v131, 12, v131
	v_add_u32_e32 v131, 0x20000, v131
	v_and_b32_e32 v132, 7, v129
	v_lshlrev_b32_e32 v133, 1, v130
	v_xor_b32_e32 v132, v133, v132
	v_lshlrev_b32_e32 v132, 4, v132
	v_lshl_add_u32 v132, v129, 8, v132
	v_add_u32_e32 v160, v131, v132
	v_xor_b32_e32 v161, 16, v160
	v_lshrrev_b32_e32 v133, 2, v128
	v_and_b32_e32 v134, 3, v128
	v_and_b32_e32 v135, 7, v133
	v_lshlrev_b32_e32 v136, 1, v134
	v_xor_b32_e32 v136, v136, v135
	v_lshlrev_b32_e32 v136, 4, v136
	v_lshl_add_u32 v136, v133, 8, v136
	v_add_u32_e32 v162, v131, v136
	v_xor_b32_e32 v163, 16, v162
	s_lshl_b32 s0, s0, 8
	s_add_i32 s0, s0, s41
	v_add_u32_e32 v137, s0, v133
	s_lshl_b32 s1, s1, 8
	s_add_i32 s1, s1, s42
	v_lshl_add_u32 v138, v134, 3, s1
	v_lshlrev_b32_e32 v139, 10, v137
	v_lshl_add_u32 v164, v138, 1, v139
	v_lshlrev_b32_e32 v139, 11, v137
	v_lshl_add_u32 v165, v138, 1, v139
	v_lshlrev_b32_e32 v139, 2, v138
	v_mov_b32_e32 v170, 1.0
	v_mov_b32_e32 v171, 1.0
	v_mov_b32_e32 v176, 0xbfb8aa3b
	v_mov_b32_e32 v177, 0xbfb8aa3b
	global_load_dwordx4 v[184:187], v139, s[6:7]
	global_load_dwordx4 v[188:191], v139, s[6:7] offset:16
	global_load_dwordx4 v[192:195], v139, s[6:7] offset:512
	global_load_dwordx4 v[196:199], v139, s[6:7] offset:528
	s_mov_b64 s[98:99], s[8:9]
	global_load_dwordx4 v[200:203], v164, s[98:99]
	global_load_dwordx4 v[204:207], v164, s[98:99] offset:256
	s_add_u32 s98, s98, 0x4000
	s_addc_u32 s99, s99, 0
	global_load_dwordx4 v[208:211], v164, s[98:99]
	global_load_dwordx4 v[212:215], v164, s[98:99] offset:256
	s_add_u32 s98, s98, 0x4000
	s_addc_u32 s99, s99, 0
	global_load_dwordx4 v[216:219], v164, s[98:99]
	global_load_dwordx4 v[220:223], v164, s[98:99] offset:256
	s_add_u32 s98, s98, 0x4000
	s_addc_u32 s99, s99, 0
	global_load_dwordx4 v[224:227], v164, s[98:99]
	global_load_dwordx4 v[228:231], v164, s[98:99] offset:256
	s_add_u32 s98, s98, 0x14000
	s_addc_u32 s99, s99, 0
	ds_write_b128 v160, v[124:127]
	ds_write_b128 v161, v[120:123]
	ds_write_b128 v160, v[60:63] offset:128
	ds_write_b128 v161, v[56:59] offset:128
	s_waitcnt lgkmcnt(0)
	ds_read_b128 v[128:131], v162
	ds_read_b128 v[132:135], v163
	ds_read_b128 v[136:139], v162 offset:128
	ds_read_b128 v[140:143], v163 offset:128
	s_waitcnt vmcnt(6)
	s_waitcnt lgkmcnt(0)
	v_pk_add_f32 v[128:129], v[128:129], v[184:185]
	v_pk_add_f32 v[130:131], v[130:131], v[186:187]
	v_pk_add_f32 v[132:133], v[132:133], v[188:189]
	v_pk_add_f32 v[134:135], v[134:135], v[190:191]
	v_pk_mul_f32 v[128:129], v[128:129], v[176:177]
	v_pk_mul_f32 v[130:131], v[130:131], v[176:177]
	v_pk_mul_f32 v[132:133], v[132:133], v[176:177]
	v_pk_mul_f32 v[134:135], v[134:135], v[176:177]
	v_exp_f32_e32 v128, v128
	v_exp_f32_e32 v129, v129
	v_exp_f32_e32 v130, v130
	v_exp_f32_e32 v131, v131
	v_exp_f32_e32 v132, v132
	v_exp_f32_e32 v133, v133
	v_exp_f32_e32 v134, v134
	v_exp_f32_e32 v135, v135
	v_lshlrev_b32_e32 v232, 16, v200
	v_and_b32_e32 v233, 0xffff0000, v200
	v_lshlrev_b32_e32 v234, 16, v201
	v_and_b32_e32 v235, 0xffff0000, v201
	v_lshlrev_b32_e32 v236, 16, v202
	v_and_b32_e32 v237, 0xffff0000, v202
	v_lshlrev_b32_e32 v238, 16, v203
	v_and_b32_e32 v239, 0xffff0000, v203
	v_pk_add_f32 v[128:129], v[128:129], v[170:171]
	v_pk_add_f32 v[130:131], v[130:131], v[170:171]
	v_pk_add_f32 v[132:133], v[132:133], v[170:171]
	v_pk_add_f32 v[134:135], v[134:135], v[170:171]
	v_rcp_f32_e32 v128, v128
	v_rcp_f32_e32 v129, v129
	v_rcp_f32_e32 v130, v130
	v_rcp_f32_e32 v131, v131
	v_rcp_f32_e32 v132, v132
	v_rcp_f32_e32 v133, v133
	v_rcp_f32_e32 v134, v134
	v_rcp_f32_e32 v135, v135
	s_nop 0
	v_pk_mul_f32 v[128:129], v[128:129], v[232:233]
	v_pk_mul_f32 v[130:131], v[130:131], v[234:235]
	v_pk_mul_f32 v[132:133], v[132:133], v[236:237]
	v_pk_mul_f32 v[134:135], v[134:135], v[238:239]
	v_cvt_pk_bf16_f32 v248, v128, v129
	v_cvt_pk_bf16_f32 v249, v130, v131
	v_cvt_pk_bf16_f32 v250, v132, v133
	v_cvt_pk_bf16_f32 v251, v134, v135
	global_store_dwordx4 v165, v[248:251], s[12:13]
	v_pk_add_f32 v[136:137], v[136:137], v[192:193]
	v_pk_add_f32 v[138:139], v[138:139], v[194:195]
	v_pk_add_f32 v[140:141], v[140:141], v[196:197]
	v_pk_add_f32 v[142:143], v[142:143], v[198:199]
	v_pk_mul_f32 v[136:137], v[136:137], v[176:177]
	v_pk_mul_f32 v[138:139], v[138:139], v[176:177]
	v_pk_mul_f32 v[140:141], v[140:141], v[176:177]
	v_pk_mul_f32 v[142:143], v[142:143], v[176:177]
	v_exp_f32_e32 v136, v136
	v_exp_f32_e32 v137, v137
	v_exp_f32_e32 v138, v138
	v_exp_f32_e32 v139, v139
	v_exp_f32_e32 v140, v140
	v_exp_f32_e32 v141, v141
	v_exp_f32_e32 v142, v142
	v_exp_f32_e32 v143, v143
	v_lshlrev_b32_e32 v232, 16, v204
	v_and_b32_e32 v233, 0xffff0000, v204
	v_lshlrev_b32_e32 v234, 16, v205
	v_and_b32_e32 v235, 0xffff0000, v205
	v_lshlrev_b32_e32 v236, 16, v206
	v_and_b32_e32 v237, 0xffff0000, v206
	v_lshlrev_b32_e32 v238, 16, v207
	v_and_b32_e32 v239, 0xffff0000, v207
	v_pk_add_f32 v[136:137], v[136:137], v[170:171]
	v_pk_add_f32 v[138:139], v[138:139], v[170:171]
	v_pk_add_f32 v[140:141], v[140:141], v[170:171]
	v_pk_add_f32 v[142:143], v[142:143], v[170:171]
	v_rcp_f32_e32 v136, v136
	v_rcp_f32_e32 v137, v137
	v_rcp_f32_e32 v138, v138
	v_rcp_f32_e32 v139, v139
	v_rcp_f32_e32 v140, v140
	v_rcp_f32_e32 v141, v141
	v_rcp_f32_e32 v142, v142
	v_rcp_f32_e32 v143, v143
	s_nop 0
	v_pk_mul_f32 v[136:137], v[136:137], v[232:233]
	v_pk_mul_f32 v[138:139], v[138:139], v[234:235]
	v_pk_mul_f32 v[140:141], v[140:141], v[236:237]
	v_pk_mul_f32 v[142:143], v[142:143], v[238:239]
	v_cvt_pk_bf16_f32 v166, v136, v137
	v_cvt_pk_bf16_f32 v167, v138, v139
	v_cvt_pk_bf16_f32 v168, v140, v141
	v_cvt_pk_bf16_f32 v169, v142, v143
	global_store_dwordx4 v165, v[166:169], s[12:13] offset:256
	global_load_dwordx4 v[200:203], v164, s[98:99]
	global_load_dwordx4 v[204:207], v164, s[98:99] offset:256
	s_add_u32 s98, s98, 0x4000
	s_addc_u32 s99, s99, 0
	v_add_u32_e32 v165, 0x8000, v165
	ds_write_b128 v160, v[116:119]
	ds_write_b128 v161, v[112:115]
	ds_write_b128 v160, v[52:55] offset:128
	ds_write_b128 v161, v[48:51] offset:128
	s_waitcnt lgkmcnt(0)
	ds_read_b128 v[128:131], v162
	ds_read_b128 v[132:135], v163
	ds_read_b128 v[136:139], v162 offset:128
	ds_read_b128 v[140:143], v163 offset:128
	s_waitcnt vmcnt(8)
	s_waitcnt lgkmcnt(0)
	v_pk_add_f32 v[128:129], v[128:129], v[184:185]
	v_pk_add_f32 v[130:131], v[130:131], v[186:187]
	v_pk_add_f32 v[132:133], v[132:133], v[188:189]
	v_pk_add_f32 v[134:135], v[134:135], v[190:191]
	v_pk_mul_f32 v[128:129], v[128:129], v[176:177]
	v_pk_mul_f32 v[130:131], v[130:131], v[176:177]
	v_pk_mul_f32 v[132:133], v[132:133], v[176:177]
	v_pk_mul_f32 v[134:135], v[134:135], v[176:177]
	v_exp_f32_e32 v128, v128
	v_exp_f32_e32 v129, v129
	v_exp_f32_e32 v130, v130
	v_exp_f32_e32 v131, v131
	v_exp_f32_e32 v132, v132
	v_exp_f32_e32 v133, v133
	v_exp_f32_e32 v134, v134
	v_exp_f32_e32 v135, v135
	v_lshlrev_b32_e32 v232, 16, v208
	v_and_b32_e32 v233, 0xffff0000, v208
	v_lshlrev_b32_e32 v234, 16, v209
	v_and_b32_e32 v235, 0xffff0000, v209
	v_lshlrev_b32_e32 v236, 16, v210
	v_and_b32_e32 v237, 0xffff0000, v210
	v_lshlrev_b32_e32 v238, 16, v211
	v_and_b32_e32 v239, 0xffff0000, v211
	v_pk_add_f32 v[128:129], v[128:129], v[170:171]
	v_pk_add_f32 v[130:131], v[130:131], v[170:171]
	v_pk_add_f32 v[132:133], v[132:133], v[170:171]
	v_pk_add_f32 v[134:135], v[134:135], v[170:171]
	v_rcp_f32_e32 v128, v128
	v_rcp_f32_e32 v129, v129
	v_rcp_f32_e32 v130, v130
	v_rcp_f32_e32 v131, v131
	v_rcp_f32_e32 v132, v132
	v_rcp_f32_e32 v133, v133
	v_rcp_f32_e32 v134, v134
	v_rcp_f32_e32 v135, v135
	s_nop 0
	v_pk_mul_f32 v[128:129], v[128:129], v[232:233]
	v_pk_mul_f32 v[130:131], v[130:131], v[234:235]
	v_pk_mul_f32 v[132:133], v[132:133], v[236:237]
	v_pk_mul_f32 v[134:135], v[134:135], v[238:239]
	v_cvt_pk_bf16_f32 v248, v128, v129
	v_cvt_pk_bf16_f32 v249, v130, v131
	v_cvt_pk_bf16_f32 v250, v132, v133
	v_cvt_pk_bf16_f32 v251, v134, v135
	global_store_dwordx4 v165, v[248:251], s[12:13]
	v_pk_add_f32 v[136:137], v[136:137], v[192:193]
	v_pk_add_f32 v[138:139], v[138:139], v[194:195]
	v_pk_add_f32 v[140:141], v[140:141], v[196:197]
	v_pk_add_f32 v[142:143], v[142:143], v[198:199]
	v_pk_mul_f32 v[136:137], v[136:137], v[176:177]
	v_pk_mul_f32 v[138:139], v[138:139], v[176:177]
	v_pk_mul_f32 v[140:141], v[140:141], v[176:177]
	v_pk_mul_f32 v[142:143], v[142:143], v[176:177]
	v_exp_f32_e32 v136, v136
	v_exp_f32_e32 v137, v137
	v_exp_f32_e32 v138, v138
	v_exp_f32_e32 v139, v139
	v_exp_f32_e32 v140, v140
	v_exp_f32_e32 v141, v141
	v_exp_f32_e32 v142, v142
	v_exp_f32_e32 v143, v143
	v_lshlrev_b32_e32 v232, 16, v212
	v_and_b32_e32 v233, 0xffff0000, v212
	v_lshlrev_b32_e32 v234, 16, v213
	v_and_b32_e32 v235, 0xffff0000, v213
	v_lshlrev_b32_e32 v236, 16, v214
	v_and_b32_e32 v237, 0xffff0000, v214
	v_lshlrev_b32_e32 v238, 16, v215
	v_and_b32_e32 v239, 0xffff0000, v215
	v_pk_add_f32 v[136:137], v[136:137], v[170:171]
	v_pk_add_f32 v[138:139], v[138:139], v[170:171]
	v_pk_add_f32 v[140:141], v[140:141], v[170:171]
	v_pk_add_f32 v[142:143], v[142:143], v[170:171]
	v_rcp_f32_e32 v136, v136
	v_rcp_f32_e32 v137, v137
	v_rcp_f32_e32 v138, v138
	v_rcp_f32_e32 v139, v139
	v_rcp_f32_e32 v140, v140
	v_rcp_f32_e32 v141, v141
	v_rcp_f32_e32 v142, v142
	v_rcp_f32_e32 v143, v143
	s_nop 0
	v_pk_mul_f32 v[136:137], v[136:137], v[232:233]
	v_pk_mul_f32 v[138:139], v[138:139], v[234:235]
	v_pk_mul_f32 v[140:141], v[140:141], v[236:237]
	v_pk_mul_f32 v[142:143], v[142:143], v[238:239]
	v_cvt_pk_bf16_f32 v166, v136, v137
	v_cvt_pk_bf16_f32 v167, v138, v139
	v_cvt_pk_bf16_f32 v168, v140, v141
	v_cvt_pk_bf16_f32 v169, v142, v143
	global_store_dwordx4 v165, v[166:169], s[12:13] offset:256
	global_load_dwordx4 v[208:211], v164, s[98:99]
	global_load_dwordx4 v[212:215], v164, s[98:99] offset:256
	s_add_u32 s98, s98, 0x4000
	s_addc_u32 s99, s99, 0
	v_add_u32_e32 v165, 0x8000, v165
	ds_write_b128 v160, v[108:111]
	ds_write_b128 v161, v[104:107]
	ds_write_b128 v160, v[44:47] offset:128
	ds_write_b128 v161, v[40:43] offset:128
	s_waitcnt lgkmcnt(0)
	ds_read_b128 v[128:131], v162
	ds_read_b128 v[132:135], v163
	ds_read_b128 v[136:139], v162 offset:128
	ds_read_b128 v[140:143], v163 offset:128
	s_waitcnt vmcnt(10)
	s_waitcnt lgkmcnt(0)
	v_pk_add_f32 v[128:129], v[128:129], v[184:185]
	v_pk_add_f32 v[130:131], v[130:131], v[186:187]
	v_pk_add_f32 v[132:133], v[132:133], v[188:189]
	v_pk_add_f32 v[134:135], v[134:135], v[190:191]
	v_pk_mul_f32 v[128:129], v[128:129], v[176:177]
	v_pk_mul_f32 v[130:131], v[130:131], v[176:177]
	v_pk_mul_f32 v[132:133], v[132:133], v[176:177]
	v_pk_mul_f32 v[134:135], v[134:135], v[176:177]
	v_exp_f32_e32 v128, v128
	v_exp_f32_e32 v129, v129
	v_exp_f32_e32 v130, v130
	v_exp_f32_e32 v131, v131
	v_exp_f32_e32 v132, v132
	v_exp_f32_e32 v133, v133
	v_exp_f32_e32 v134, v134
	v_exp_f32_e32 v135, v135
	v_lshlrev_b32_e32 v232, 16, v216
	v_and_b32_e32 v233, 0xffff0000, v216
	v_lshlrev_b32_e32 v234, 16, v217
	v_and_b32_e32 v235, 0xffff0000, v217
	v_lshlrev_b32_e32 v236, 16, v218
	v_and_b32_e32 v237, 0xffff0000, v218
	v_lshlrev_b32_e32 v238, 16, v219
	v_and_b32_e32 v239, 0xffff0000, v219
	v_pk_add_f32 v[128:129], v[128:129], v[170:171]
	v_pk_add_f32 v[130:131], v[130:131], v[170:171]
	v_pk_add_f32 v[132:133], v[132:133], v[170:171]
	v_pk_add_f32 v[134:135], v[134:135], v[170:171]
	v_rcp_f32_e32 v128, v128
	v_rcp_f32_e32 v129, v129
	v_rcp_f32_e32 v130, v130
	v_rcp_f32_e32 v131, v131
	v_rcp_f32_e32 v132, v132
	v_rcp_f32_e32 v133, v133
	v_rcp_f32_e32 v134, v134
	v_rcp_f32_e32 v135, v135
	s_nop 0
	v_pk_mul_f32 v[128:129], v[128:129], v[232:233]
	v_pk_mul_f32 v[130:131], v[130:131], v[234:235]
	v_pk_mul_f32 v[132:133], v[132:133], v[236:237]
	v_pk_mul_f32 v[134:135], v[134:135], v[238:239]
	v_cvt_pk_bf16_f32 v248, v128, v129
	v_cvt_pk_bf16_f32 v249, v130, v131
	v_cvt_pk_bf16_f32 v250, v132, v133
	v_cvt_pk_bf16_f32 v251, v134, v135
	global_store_dwordx4 v165, v[248:251], s[12:13]
	v_pk_add_f32 v[136:137], v[136:137], v[192:193]
	v_pk_add_f32 v[138:139], v[138:139], v[194:195]
	v_pk_add_f32 v[140:141], v[140:141], v[196:197]
	v_pk_add_f32 v[142:143], v[142:143], v[198:199]
	v_pk_mul_f32 v[136:137], v[136:137], v[176:177]
	v_pk_mul_f32 v[138:139], v[138:139], v[176:177]
	v_pk_mul_f32 v[140:141], v[140:141], v[176:177]
	v_pk_mul_f32 v[142:143], v[142:143], v[176:177]
	v_exp_f32_e32 v136, v136
	v_exp_f32_e32 v137, v137
	v_exp_f32_e32 v138, v138
	v_exp_f32_e32 v139, v139
	v_exp_f32_e32 v140, v140
	v_exp_f32_e32 v141, v141
	v_exp_f32_e32 v142, v142
	v_exp_f32_e32 v143, v143
	v_lshlrev_b32_e32 v232, 16, v220
	v_and_b32_e32 v233, 0xffff0000, v220
	v_lshlrev_b32_e32 v234, 16, v221
	v_and_b32_e32 v235, 0xffff0000, v221
	v_lshlrev_b32_e32 v236, 16, v222
	v_and_b32_e32 v237, 0xffff0000, v222
	v_lshlrev_b32_e32 v238, 16, v223
	v_and_b32_e32 v239, 0xffff0000, v223
	v_pk_add_f32 v[136:137], v[136:137], v[170:171]
	v_pk_add_f32 v[138:139], v[138:139], v[170:171]
	v_pk_add_f32 v[140:141], v[140:141], v[170:171]
	v_pk_add_f32 v[142:143], v[142:143], v[170:171]
	v_rcp_f32_e32 v136, v136
	v_rcp_f32_e32 v137, v137
	v_rcp_f32_e32 v138, v138
	v_rcp_f32_e32 v139, v139
	v_rcp_f32_e32 v140, v140
	v_rcp_f32_e32 v141, v141
	v_rcp_f32_e32 v142, v142
	v_rcp_f32_e32 v143, v143
	s_nop 0
	v_pk_mul_f32 v[136:137], v[136:137], v[232:233]
	v_pk_mul_f32 v[138:139], v[138:139], v[234:235]
	v_pk_mul_f32 v[140:141], v[140:141], v[236:237]
	v_pk_mul_f32 v[142:143], v[142:143], v[238:239]
	v_cvt_pk_bf16_f32 v166, v136, v137
	v_cvt_pk_bf16_f32 v167, v138, v139
	v_cvt_pk_bf16_f32 v168, v140, v141
	v_cvt_pk_bf16_f32 v169, v142, v143
	global_store_dwordx4 v165, v[166:169], s[12:13] offset:256
	global_load_dwordx4 v[216:219], v164, s[98:99]
	global_load_dwordx4 v[220:223], v164, s[98:99] offset:256
	s_add_u32 s98, s98, 0x4000
	s_addc_u32 s99, s99, 0
	v_add_u32_e32 v165, 0x8000, v165
	ds_write_b128 v160, v[100:103]
	ds_write_b128 v161, v[96:99]
	ds_write_b128 v160, v[36:39] offset:128
	ds_write_b128 v161, v[32:35] offset:128
	s_waitcnt lgkmcnt(0)
	ds_read_b128 v[128:131], v162
	ds_read_b128 v[132:135], v163
	ds_read_b128 v[136:139], v162 offset:128
	ds_read_b128 v[140:143], v163 offset:128
	s_waitcnt vmcnt(12)
	s_waitcnt lgkmcnt(0)
	v_pk_add_f32 v[128:129], v[128:129], v[184:185]
	v_pk_add_f32 v[130:131], v[130:131], v[186:187]
	v_pk_add_f32 v[132:133], v[132:133], v[188:189]
	v_pk_add_f32 v[134:135], v[134:135], v[190:191]
	v_pk_mul_f32 v[128:129], v[128:129], v[176:177]
	v_pk_mul_f32 v[130:131], v[130:131], v[176:177]
	v_pk_mul_f32 v[132:133], v[132:133], v[176:177]
	v_pk_mul_f32 v[134:135], v[134:135], v[176:177]
	v_exp_f32_e32 v128, v128
	v_exp_f32_e32 v129, v129
	v_exp_f32_e32 v130, v130
	v_exp_f32_e32 v131, v131
	v_exp_f32_e32 v132, v132
	v_exp_f32_e32 v133, v133
	v_exp_f32_e32 v134, v134
	v_exp_f32_e32 v135, v135
	v_lshlrev_b32_e32 v232, 16, v224
	v_and_b32_e32 v233, 0xffff0000, v224
	v_lshlrev_b32_e32 v234, 16, v225
	v_and_b32_e32 v235, 0xffff0000, v225
	v_lshlrev_b32_e32 v236, 16, v226
	v_and_b32_e32 v237, 0xffff0000, v226
	v_lshlrev_b32_e32 v238, 16, v227
	v_and_b32_e32 v239, 0xffff0000, v227
	v_pk_add_f32 v[128:129], v[128:129], v[170:171]
	v_pk_add_f32 v[130:131], v[130:131], v[170:171]
	v_pk_add_f32 v[132:133], v[132:133], v[170:171]
	v_pk_add_f32 v[134:135], v[134:135], v[170:171]
	v_rcp_f32_e32 v128, v128
	v_rcp_f32_e32 v129, v129
	v_rcp_f32_e32 v130, v130
	v_rcp_f32_e32 v131, v131
	v_rcp_f32_e32 v132, v132
	v_rcp_f32_e32 v133, v133
	v_rcp_f32_e32 v134, v134
	v_rcp_f32_e32 v135, v135
	s_nop 0
	v_pk_mul_f32 v[128:129], v[128:129], v[232:233]
	v_pk_mul_f32 v[130:131], v[130:131], v[234:235]
	v_pk_mul_f32 v[132:133], v[132:133], v[236:237]
	v_pk_mul_f32 v[134:135], v[134:135], v[238:239]
	v_cvt_pk_bf16_f32 v248, v128, v129
	v_cvt_pk_bf16_f32 v249, v130, v131
	v_cvt_pk_bf16_f32 v250, v132, v133
	v_cvt_pk_bf16_f32 v251, v134, v135
	global_store_dwordx4 v165, v[248:251], s[12:13]
	v_pk_add_f32 v[136:137], v[136:137], v[192:193]
	v_pk_add_f32 v[138:139], v[138:139], v[194:195]
	v_pk_add_f32 v[140:141], v[140:141], v[196:197]
	v_pk_add_f32 v[142:143], v[142:143], v[198:199]
	v_pk_mul_f32 v[136:137], v[136:137], v[176:177]
	v_pk_mul_f32 v[138:139], v[138:139], v[176:177]
	v_pk_mul_f32 v[140:141], v[140:141], v[176:177]
	v_pk_mul_f32 v[142:143], v[142:143], v[176:177]
	v_exp_f32_e32 v136, v136
	v_exp_f32_e32 v137, v137
	v_exp_f32_e32 v138, v138
	v_exp_f32_e32 v139, v139
	v_exp_f32_e32 v140, v140
	v_exp_f32_e32 v141, v141
	v_exp_f32_e32 v142, v142
	v_exp_f32_e32 v143, v143
	v_lshlrev_b32_e32 v232, 16, v228
	v_and_b32_e32 v233, 0xffff0000, v228
	v_lshlrev_b32_e32 v234, 16, v229
	v_and_b32_e32 v235, 0xffff0000, v229
	v_lshlrev_b32_e32 v236, 16, v230
	v_and_b32_e32 v237, 0xffff0000, v230
	v_lshlrev_b32_e32 v238, 16, v231
	v_and_b32_e32 v239, 0xffff0000, v231
	v_pk_add_f32 v[136:137], v[136:137], v[170:171]
	v_pk_add_f32 v[138:139], v[138:139], v[170:171]
	v_pk_add_f32 v[140:141], v[140:141], v[170:171]
	v_pk_add_f32 v[142:143], v[142:143], v[170:171]
	v_rcp_f32_e32 v136, v136
	v_rcp_f32_e32 v137, v137
	v_rcp_f32_e32 v138, v138
	v_rcp_f32_e32 v139, v139
	v_rcp_f32_e32 v140, v140
	v_rcp_f32_e32 v141, v141
	v_rcp_f32_e32 v142, v142
	v_rcp_f32_e32 v143, v143
	s_nop 0
	v_pk_mul_f32 v[136:137], v[136:137], v[232:233]
	v_pk_mul_f32 v[138:139], v[138:139], v[234:235]
	v_pk_mul_f32 v[140:141], v[140:141], v[236:237]
	v_pk_mul_f32 v[142:143], v[142:143], v[238:239]
	v_cvt_pk_bf16_f32 v166, v136, v137
	v_cvt_pk_bf16_f32 v167, v138, v139
	v_cvt_pk_bf16_f32 v168, v140, v141
	v_cvt_pk_bf16_f32 v169, v142, v143
	global_store_dwordx4 v165, v[166:169], s[12:13] offset:256
	global_load_dwordx4 v[224:227], v164, s[98:99]
	global_load_dwordx4 v[228:231], v164, s[98:99] offset:256
	v_add_u32_e32 v165, 0x28000, v165
	ds_write_b128 v160, v[92:95]
	ds_write_b128 v161, v[88:91]
	ds_write_b128 v160, v[28:31] offset:128
	ds_write_b128 v161, v[24:27] offset:128
	s_waitcnt lgkmcnt(0)
	ds_read_b128 v[128:131], v162
	ds_read_b128 v[132:135], v163
	ds_read_b128 v[136:139], v162 offset:128
	ds_read_b128 v[140:143], v163 offset:128
	s_waitcnt vmcnt(12)
	s_waitcnt lgkmcnt(0)
	v_pk_add_f32 v[128:129], v[128:129], v[184:185]
	v_pk_add_f32 v[130:131], v[130:131], v[186:187]
	v_pk_add_f32 v[132:133], v[132:133], v[188:189]
	v_pk_add_f32 v[134:135], v[134:135], v[190:191]
	v_pk_mul_f32 v[128:129], v[128:129], v[176:177]
	v_pk_mul_f32 v[130:131], v[130:131], v[176:177]
	v_pk_mul_f32 v[132:133], v[132:133], v[176:177]
	v_pk_mul_f32 v[134:135], v[134:135], v[176:177]
	v_exp_f32_e32 v128, v128
	v_exp_f32_e32 v129, v129
	v_exp_f32_e32 v130, v130
	v_exp_f32_e32 v131, v131
	v_exp_f32_e32 v132, v132
	v_exp_f32_e32 v133, v133
	v_exp_f32_e32 v134, v134
	v_exp_f32_e32 v135, v135
	v_lshlrev_b32_e32 v232, 16, v200
	v_and_b32_e32 v233, 0xffff0000, v200
	v_lshlrev_b32_e32 v234, 16, v201
	v_and_b32_e32 v235, 0xffff0000, v201
	v_lshlrev_b32_e32 v236, 16, v202
	v_and_b32_e32 v237, 0xffff0000, v202
	v_lshlrev_b32_e32 v238, 16, v203
	v_and_b32_e32 v239, 0xffff0000, v203
	v_pk_add_f32 v[128:129], v[128:129], v[170:171]
	v_pk_add_f32 v[130:131], v[130:131], v[170:171]
	v_pk_add_f32 v[132:133], v[132:133], v[170:171]
	v_pk_add_f32 v[134:135], v[134:135], v[170:171]
	v_rcp_f32_e32 v128, v128
	v_rcp_f32_e32 v129, v129
	v_rcp_f32_e32 v130, v130
	v_rcp_f32_e32 v131, v131
	v_rcp_f32_e32 v132, v132
	v_rcp_f32_e32 v133, v133
	v_rcp_f32_e32 v134, v134
	v_rcp_f32_e32 v135, v135
	s_nop 0
	v_pk_mul_f32 v[128:129], v[128:129], v[232:233]
	v_pk_mul_f32 v[130:131], v[130:131], v[234:235]
	v_pk_mul_f32 v[132:133], v[132:133], v[236:237]
	v_pk_mul_f32 v[134:135], v[134:135], v[238:239]
	v_cvt_pk_bf16_f32 v248, v128, v129
	v_cvt_pk_bf16_f32 v249, v130, v131
	v_cvt_pk_bf16_f32 v250, v132, v133
	v_cvt_pk_bf16_f32 v251, v134, v135
	global_store_dwordx4 v165, v[248:251], s[12:13]
	v_pk_add_f32 v[136:137], v[136:137], v[192:193]
	v_pk_add_f32 v[138:139], v[138:139], v[194:195]
	v_pk_add_f32 v[140:141], v[140:141], v[196:197]
	v_pk_add_f32 v[142:143], v[142:143], v[198:199]
	v_pk_mul_f32 v[136:137], v[136:137], v[176:177]
	v_pk_mul_f32 v[138:139], v[138:139], v[176:177]
	v_pk_mul_f32 v[140:141], v[140:141], v[176:177]
	v_pk_mul_f32 v[142:143], v[142:143], v[176:177]
	v_exp_f32_e32 v136, v136
	v_exp_f32_e32 v137, v137
	v_exp_f32_e32 v138, v138
	v_exp_f32_e32 v139, v139
	v_exp_f32_e32 v140, v140
	v_exp_f32_e32 v141, v141
	v_exp_f32_e32 v142, v142
	v_exp_f32_e32 v143, v143
	v_lshlrev_b32_e32 v232, 16, v204
	v_and_b32_e32 v233, 0xffff0000, v204
	v_lshlrev_b32_e32 v234, 16, v205
	v_and_b32_e32 v235, 0xffff0000, v205
	v_lshlrev_b32_e32 v236, 16, v206
	v_and_b32_e32 v237, 0xffff0000, v206
	v_lshlrev_b32_e32 v238, 16, v207
	v_and_b32_e32 v239, 0xffff0000, v207
	v_pk_add_f32 v[136:137], v[136:137], v[170:171]
	v_pk_add_f32 v[138:139], v[138:139], v[170:171]
	v_pk_add_f32 v[140:141], v[140:141], v[170:171]
	v_pk_add_f32 v[142:143], v[142:143], v[170:171]
	v_rcp_f32_e32 v136, v136
	v_rcp_f32_e32 v137, v137
	v_rcp_f32_e32 v138, v138
	v_rcp_f32_e32 v139, v139
	v_rcp_f32_e32 v140, v140
	v_rcp_f32_e32 v141, v141
	v_rcp_f32_e32 v142, v142
	v_rcp_f32_e32 v143, v143
	s_nop 0
	v_pk_mul_f32 v[136:137], v[136:137], v[232:233]
	v_pk_mul_f32 v[138:139], v[138:139], v[234:235]
	v_pk_mul_f32 v[140:141], v[140:141], v[236:237]
	v_pk_mul_f32 v[142:143], v[142:143], v[238:239]
	v_cvt_pk_bf16_f32 v166, v136, v137
	v_cvt_pk_bf16_f32 v167, v138, v139
	v_cvt_pk_bf16_f32 v168, v140, v141
	v_cvt_pk_bf16_f32 v169, v142, v143
	global_store_dwordx4 v165, v[166:169], s[12:13] offset:256
	v_add_u32_e32 v165, 0x8000, v165
	ds_write_b128 v160, v[84:87]
	ds_write_b128 v161, v[80:83]
	ds_write_b128 v160, v[20:23] offset:128
	ds_write_b128 v161, v[16:19] offset:128
	s_waitcnt lgkmcnt(0)
	ds_read_b128 v[128:131], v162
	ds_read_b128 v[132:135], v163
	ds_read_b128 v[136:139], v162 offset:128
	ds_read_b128 v[140:143], v163 offset:128
	s_waitcnt vmcnt(10)
	s_waitcnt lgkmcnt(0)
	v_pk_add_f32 v[128:129], v[128:129], v[184:185]
	v_pk_add_f32 v[130:131], v[130:131], v[186:187]
	v_pk_add_f32 v[132:133], v[132:133], v[188:189]
	v_pk_add_f32 v[134:135], v[134:135], v[190:191]
	v_pk_mul_f32 v[128:129], v[128:129], v[176:177]
	v_pk_mul_f32 v[130:131], v[130:131], v[176:177]
	v_pk_mul_f32 v[132:133], v[132:133], v[176:177]
	v_pk_mul_f32 v[134:135], v[134:135], v[176:177]
	v_exp_f32_e32 v128, v128
	v_exp_f32_e32 v129, v129
	v_exp_f32_e32 v130, v130
	v_exp_f32_e32 v131, v131
	v_exp_f32_e32 v132, v132
	v_exp_f32_e32 v133, v133
	v_exp_f32_e32 v134, v134
	v_exp_f32_e32 v135, v135
	v_lshlrev_b32_e32 v232, 16, v208
	v_and_b32_e32 v233, 0xffff0000, v208
	v_lshlrev_b32_e32 v234, 16, v209
	v_and_b32_e32 v235, 0xffff0000, v209
	v_lshlrev_b32_e32 v236, 16, v210
	v_and_b32_e32 v237, 0xffff0000, v210
	v_lshlrev_b32_e32 v238, 16, v211
	v_and_b32_e32 v239, 0xffff0000, v211
	v_pk_add_f32 v[128:129], v[128:129], v[170:171]
	v_pk_add_f32 v[130:131], v[130:131], v[170:171]
	v_pk_add_f32 v[132:133], v[132:133], v[170:171]
	v_pk_add_f32 v[134:135], v[134:135], v[170:171]
	v_rcp_f32_e32 v128, v128
	v_rcp_f32_e32 v129, v129
	v_rcp_f32_e32 v130, v130
	v_rcp_f32_e32 v131, v131
	v_rcp_f32_e32 v132, v132
	v_rcp_f32_e32 v133, v133
	v_rcp_f32_e32 v134, v134
	v_rcp_f32_e32 v135, v135
	s_nop 0
	v_pk_mul_f32 v[128:129], v[128:129], v[232:233]
	v_pk_mul_f32 v[130:131], v[130:131], v[234:235]
	v_pk_mul_f32 v[132:133], v[132:133], v[236:237]
	v_pk_mul_f32 v[134:135], v[134:135], v[238:239]
	v_cvt_pk_bf16_f32 v248, v128, v129
	v_cvt_pk_bf16_f32 v249, v130, v131
	v_cvt_pk_bf16_f32 v250, v132, v133
	v_cvt_pk_bf16_f32 v251, v134, v135
	global_store_dwordx4 v165, v[248:251], s[12:13]
	v_pk_add_f32 v[136:137], v[136:137], v[192:193]
	v_pk_add_f32 v[138:139], v[138:139], v[194:195]
	v_pk_add_f32 v[140:141], v[140:141], v[196:197]
	v_pk_add_f32 v[142:143], v[142:143], v[198:199]
	v_pk_mul_f32 v[136:137], v[136:137], v[176:177]
	v_pk_mul_f32 v[138:139], v[138:139], v[176:177]
	v_pk_mul_f32 v[140:141], v[140:141], v[176:177]
	v_pk_mul_f32 v[142:143], v[142:143], v[176:177]
	v_exp_f32_e32 v136, v136
	v_exp_f32_e32 v137, v137
	v_exp_f32_e32 v138, v138
	v_exp_f32_e32 v139, v139
	v_exp_f32_e32 v140, v140
	v_exp_f32_e32 v141, v141
	v_exp_f32_e32 v142, v142
	v_exp_f32_e32 v143, v143
	v_lshlrev_b32_e32 v232, 16, v212
	v_and_b32_e32 v233, 0xffff0000, v212
	v_lshlrev_b32_e32 v234, 16, v213
	v_and_b32_e32 v235, 0xffff0000, v213
	v_lshlrev_b32_e32 v236, 16, v214
	v_and_b32_e32 v237, 0xffff0000, v214
	v_lshlrev_b32_e32 v238, 16, v215
	v_and_b32_e32 v239, 0xffff0000, v215
	v_pk_add_f32 v[136:137], v[136:137], v[170:171]
	v_pk_add_f32 v[138:139], v[138:139], v[170:171]
	v_pk_add_f32 v[140:141], v[140:141], v[170:171]
	v_pk_add_f32 v[142:143], v[142:143], v[170:171]
	v_rcp_f32_e32 v136, v136
	v_rcp_f32_e32 v137, v137
	v_rcp_f32_e32 v138, v138
	v_rcp_f32_e32 v139, v139
	v_rcp_f32_e32 v140, v140
	v_rcp_f32_e32 v141, v141
	v_rcp_f32_e32 v142, v142
	v_rcp_f32_e32 v143, v143
	s_nop 0
	v_pk_mul_f32 v[136:137], v[136:137], v[232:233]
	v_pk_mul_f32 v[138:139], v[138:139], v[234:235]
	v_pk_mul_f32 v[140:141], v[140:141], v[236:237]
	v_pk_mul_f32 v[142:143], v[142:143], v[238:239]
	v_cvt_pk_bf16_f32 v166, v136, v137
	v_cvt_pk_bf16_f32 v167, v138, v139
	v_cvt_pk_bf16_f32 v168, v140, v141
	v_cvt_pk_bf16_f32 v169, v142, v143
	global_store_dwordx4 v165, v[166:169], s[12:13] offset:256
	v_add_u32_e32 v165, 0x8000, v165
	ds_write_b128 v160, v[76:79]
	ds_write_b128 v161, v[72:75]
	ds_write_b128 v160, v[12:15] offset:128
	ds_write_b128 v161, v[8:11] offset:128
	s_waitcnt lgkmcnt(0)
	ds_read_b128 v[128:131], v162
	ds_read_b128 v[132:135], v163
	ds_read_b128 v[136:139], v162 offset:128
	ds_read_b128 v[140:143], v163 offset:128
	s_waitcnt vmcnt(8)
	s_waitcnt lgkmcnt(0)
	v_pk_add_f32 v[128:129], v[128:129], v[184:185]
	v_pk_add_f32 v[130:131], v[130:131], v[186:187]
	v_pk_add_f32 v[132:133], v[132:133], v[188:189]
	v_pk_add_f32 v[134:135], v[134:135], v[190:191]
	v_pk_mul_f32 v[128:129], v[128:129], v[176:177]
	v_pk_mul_f32 v[130:131], v[130:131], v[176:177]
	v_pk_mul_f32 v[132:133], v[132:133], v[176:177]
	v_pk_mul_f32 v[134:135], v[134:135], v[176:177]
	v_exp_f32_e32 v128, v128
	v_exp_f32_e32 v129, v129
	v_exp_f32_e32 v130, v130
	v_exp_f32_e32 v131, v131
	v_exp_f32_e32 v132, v132
	v_exp_f32_e32 v133, v133
	v_exp_f32_e32 v134, v134
	v_exp_f32_e32 v135, v135
	v_lshlrev_b32_e32 v232, 16, v216
	v_and_b32_e32 v233, 0xffff0000, v216
	v_lshlrev_b32_e32 v234, 16, v217
	v_and_b32_e32 v235, 0xffff0000, v217
	v_lshlrev_b32_e32 v236, 16, v218
	v_and_b32_e32 v237, 0xffff0000, v218
	v_lshlrev_b32_e32 v238, 16, v219
	v_and_b32_e32 v239, 0xffff0000, v219
	v_pk_add_f32 v[128:129], v[128:129], v[170:171]
	v_pk_add_f32 v[130:131], v[130:131], v[170:171]
	v_pk_add_f32 v[132:133], v[132:133], v[170:171]
	v_pk_add_f32 v[134:135], v[134:135], v[170:171]
	v_rcp_f32_e32 v128, v128
	v_rcp_f32_e32 v129, v129
	v_rcp_f32_e32 v130, v130
	v_rcp_f32_e32 v131, v131
	v_rcp_f32_e32 v132, v132
	v_rcp_f32_e32 v133, v133
	v_rcp_f32_e32 v134, v134
	v_rcp_f32_e32 v135, v135
	s_nop 0
	v_pk_mul_f32 v[128:129], v[128:129], v[232:233]
	v_pk_mul_f32 v[130:131], v[130:131], v[234:235]
	v_pk_mul_f32 v[132:133], v[132:133], v[236:237]
	v_pk_mul_f32 v[134:135], v[134:135], v[238:239]
	v_cvt_pk_bf16_f32 v248, v128, v129
	v_cvt_pk_bf16_f32 v249, v130, v131
	v_cvt_pk_bf16_f32 v250, v132, v133
	v_cvt_pk_bf16_f32 v251, v134, v135
	global_store_dwordx4 v165, v[248:251], s[12:13]
	v_pk_add_f32 v[136:137], v[136:137], v[192:193]
	v_pk_add_f32 v[138:139], v[138:139], v[194:195]
	v_pk_add_f32 v[140:141], v[140:141], v[196:197]
	v_pk_add_f32 v[142:143], v[142:143], v[198:199]
	v_pk_mul_f32 v[136:137], v[136:137], v[176:177]
	v_pk_mul_f32 v[138:139], v[138:139], v[176:177]
	v_pk_mul_f32 v[140:141], v[140:141], v[176:177]
	v_pk_mul_f32 v[142:143], v[142:143], v[176:177]
	v_exp_f32_e32 v136, v136
	v_exp_f32_e32 v137, v137
	v_exp_f32_e32 v138, v138
	v_exp_f32_e32 v139, v139
	v_exp_f32_e32 v140, v140
	v_exp_f32_e32 v141, v141
	v_exp_f32_e32 v142, v142
	v_exp_f32_e32 v143, v143
	v_lshlrev_b32_e32 v232, 16, v220
	v_and_b32_e32 v233, 0xffff0000, v220
	v_lshlrev_b32_e32 v234, 16, v221
	v_and_b32_e32 v235, 0xffff0000, v221
	v_lshlrev_b32_e32 v236, 16, v222
	v_and_b32_e32 v237, 0xffff0000, v222
	v_lshlrev_b32_e32 v238, 16, v223
	v_and_b32_e32 v239, 0xffff0000, v223
	v_pk_add_f32 v[136:137], v[136:137], v[170:171]
	v_pk_add_f32 v[138:139], v[138:139], v[170:171]
	v_pk_add_f32 v[140:141], v[140:141], v[170:171]
	v_pk_add_f32 v[142:143], v[142:143], v[170:171]
	v_rcp_f32_e32 v136, v136
	v_rcp_f32_e32 v137, v137
	v_rcp_f32_e32 v138, v138
	v_rcp_f32_e32 v139, v139
	v_rcp_f32_e32 v140, v140
	v_rcp_f32_e32 v141, v141
	v_rcp_f32_e32 v142, v142
	v_rcp_f32_e32 v143, v143
	s_nop 0
	v_pk_mul_f32 v[136:137], v[136:137], v[232:233]
	v_pk_mul_f32 v[138:139], v[138:139], v[234:235]
	v_pk_mul_f32 v[140:141], v[140:141], v[236:237]
	v_pk_mul_f32 v[142:143], v[142:143], v[238:239]
	v_cvt_pk_bf16_f32 v166, v136, v137
	v_cvt_pk_bf16_f32 v167, v138, v139
	v_cvt_pk_bf16_f32 v168, v140, v141
	v_cvt_pk_bf16_f32 v169, v142, v143
	global_store_dwordx4 v165, v[166:169], s[12:13] offset:256
	v_add_u32_e32 v165, 0x8000, v165
	ds_write_b128 v160, v[68:71]
	ds_write_b128 v161, v[64:67]
	ds_write_b128 v160, v[4:7] offset:128
	ds_write_b128 v161, v[0:3] offset:128
	s_waitcnt lgkmcnt(0)
	ds_read_b128 v[128:131], v162
	ds_read_b128 v[132:135], v163
	ds_read_b128 v[136:139], v162 offset:128
	ds_read_b128 v[140:143], v163 offset:128
	s_waitcnt vmcnt(6)
	s_waitcnt lgkmcnt(0)
	v_pk_add_f32 v[128:129], v[128:129], v[184:185]
	v_pk_add_f32 v[130:131], v[130:131], v[186:187]
	v_pk_add_f32 v[132:133], v[132:133], v[188:189]
	v_pk_add_f32 v[134:135], v[134:135], v[190:191]
	v_pk_mul_f32 v[128:129], v[128:129], v[176:177]
	v_pk_mul_f32 v[130:131], v[130:131], v[176:177]
	v_pk_mul_f32 v[132:133], v[132:133], v[176:177]
	v_pk_mul_f32 v[134:135], v[134:135], v[176:177]
	v_exp_f32_e32 v128, v128
	v_exp_f32_e32 v129, v129
	v_exp_f32_e32 v130, v130
	v_exp_f32_e32 v131, v131
	v_exp_f32_e32 v132, v132
	v_exp_f32_e32 v133, v133
	v_exp_f32_e32 v134, v134
	v_exp_f32_e32 v135, v135
	v_lshlrev_b32_e32 v232, 16, v224
	v_and_b32_e32 v233, 0xffff0000, v224
	v_lshlrev_b32_e32 v234, 16, v225
	v_and_b32_e32 v235, 0xffff0000, v225
	v_lshlrev_b32_e32 v236, 16, v226
	v_and_b32_e32 v237, 0xffff0000, v226
	v_lshlrev_b32_e32 v238, 16, v227
	v_and_b32_e32 v239, 0xffff0000, v227
	v_pk_add_f32 v[128:129], v[128:129], v[170:171]
	v_pk_add_f32 v[130:131], v[130:131], v[170:171]
	v_pk_add_f32 v[132:133], v[132:133], v[170:171]
	v_pk_add_f32 v[134:135], v[134:135], v[170:171]
	v_rcp_f32_e32 v128, v128
	v_rcp_f32_e32 v129, v129
	v_rcp_f32_e32 v130, v130
	v_rcp_f32_e32 v131, v131
	v_rcp_f32_e32 v132, v132
	v_rcp_f32_e32 v133, v133
	v_rcp_f32_e32 v134, v134
	v_rcp_f32_e32 v135, v135
	s_nop 0
	v_pk_mul_f32 v[128:129], v[128:129], v[232:233]
	v_pk_mul_f32 v[130:131], v[130:131], v[234:235]
	v_pk_mul_f32 v[132:133], v[132:133], v[236:237]
	v_pk_mul_f32 v[134:135], v[134:135], v[238:239]
	v_cvt_pk_bf16_f32 v248, v128, v129
	v_cvt_pk_bf16_f32 v249, v130, v131
	v_cvt_pk_bf16_f32 v250, v132, v133
	v_cvt_pk_bf16_f32 v251, v134, v135
	global_store_dwordx4 v165, v[248:251], s[12:13]
	v_pk_add_f32 v[136:137], v[136:137], v[192:193]
	v_pk_add_f32 v[138:139], v[138:139], v[194:195]
	v_pk_add_f32 v[140:141], v[140:141], v[196:197]
	v_pk_add_f32 v[142:143], v[142:143], v[198:199]
	v_pk_mul_f32 v[136:137], v[136:137], v[176:177]
	v_pk_mul_f32 v[138:139], v[138:139], v[176:177]
	v_pk_mul_f32 v[140:141], v[140:141], v[176:177]
	v_pk_mul_f32 v[142:143], v[142:143], v[176:177]
	v_exp_f32_e32 v136, v136
	v_exp_f32_e32 v137, v137
	v_exp_f32_e32 v138, v138
	v_exp_f32_e32 v139, v139
	v_exp_f32_e32 v140, v140
	v_exp_f32_e32 v141, v141
	v_exp_f32_e32 v142, v142
	v_exp_f32_e32 v143, v143
	v_lshlrev_b32_e32 v232, 16, v228
	v_and_b32_e32 v233, 0xffff0000, v228
	v_lshlrev_b32_e32 v234, 16, v229
	v_and_b32_e32 v235, 0xffff0000, v229
	v_lshlrev_b32_e32 v236, 16, v230
	v_and_b32_e32 v237, 0xffff0000, v230
	v_lshlrev_b32_e32 v238, 16, v231
	v_and_b32_e32 v239, 0xffff0000, v231
	v_pk_add_f32 v[136:137], v[136:137], v[170:171]
	v_pk_add_f32 v[138:139], v[138:139], v[170:171]
	v_pk_add_f32 v[140:141], v[140:141], v[170:171]
	v_pk_add_f32 v[142:143], v[142:143], v[170:171]
	v_rcp_f32_e32 v136, v136
	v_rcp_f32_e32 v137, v137
	v_rcp_f32_e32 v138, v138
	v_rcp_f32_e32 v139, v139
	v_rcp_f32_e32 v140, v140
	v_rcp_f32_e32 v141, v141
	v_rcp_f32_e32 v142, v142
	v_rcp_f32_e32 v143, v143
	s_nop 0
	v_pk_mul_f32 v[136:137], v[136:137], v[232:233]
	v_pk_mul_f32 v[138:139], v[138:139], v[234:235]
	v_pk_mul_f32 v[140:141], v[140:141], v[236:237]
	v_pk_mul_f32 v[142:143], v[142:143], v[238:239]
	v_cvt_pk_bf16_f32 v166, v136, v137
	v_cvt_pk_bf16_f32 v167, v138, v139
	v_cvt_pk_bf16_f32 v168, v140, v141
	v_cvt_pk_bf16_f32 v169, v142, v143
	global_store_dwordx4 v165, v[166:169], s[12:13] offset:256
	s_andn2_b64 vcc, exec, s[4:5]
	s_mov_b64 s[0:1], -1
	s_cbranch_vccnz .LBB0_1396
	s_andn2_b64 vcc, exec, s[10:11]
	s_cbranch_vccnz .LBB0_1395
	s_barrier
	s_branch .LBB0_1395
